# v93 plus attention-branch combine loop: the 24 loads of each 4-element trip issued together
# speedup vs baseline: 1.0136x; 1.0070x over previous
.LBB0_1018:
	v_ashrrev_i32_e32 v4, 7, v6
	v_ashrrev_i32_e32 v5, 31, v4
	v_lshlrev_b64 v[2:3], 6, v[4:5]
	v_lshrrev_b32_e32 v8, 1, v6
	v_and_b32_e32 v82, 56, v8
	v_lshl_add_u64 v[8:9], s[12:13], 0, v[2:3]
	v_lshl_add_u64 v[10:11], s[14:15], 0, v[2:3]
	v_lshl_add_u64 v[2:3], s[16:17], 0, v[2:3]
	v_lshl_add_u64 v[8:9], v[8:9], 0, v[82:83]
	v_lshl_add_u64 v[10:11], v[10:11], 0, v[82:83]
	v_lshl_add_u64 v[2:3], v[2:3], 0, v[82:83]
	global_load_dwordx2 v[34:35], v[8:9], off
	global_load_dwordx2 v[40:41], v[8:9], off offset:256
	global_load_dwordx2 v[46:47], v[8:9], off offset:512
	global_load_dwordx2 v[52:53], v[8:9], off offset:768
	global_load_dwordx2 v[36:37], v[10:11], off
	global_load_dwordx2 v[42:43], v[10:11], off offset:256
	global_load_dwordx2 v[48:49], v[10:11], off offset:512
	global_load_dwordx2 v[54:55], v[10:11], off offset:768
	global_load_dwordx2 v[38:39], v[2:3], off
	global_load_dwordx2 v[44:45], v[2:3], off offset:256
	global_load_dwordx2 v[50:51], v[2:3], off offset:512
	global_load_dwordx2 v[56:57], v[2:3], off offset:768
	v_lshlrev_b64 v[64:65], 11, v[4:5]
	v_lshl_add_u64 v[64:65], s[10:11], 0, v[64:65]
	v_and_b32_e32 v72, 0x3f8, v7
	v_lshlrev_b32_e32 v72, 1, v72
	v_mov_b32_e32 v73, 0
	v_lshl_add_u64 v[64:65], v[64:65], 0, v[72:73]
	v_mov_b32_e32 v72, s56
	v_lshl_add_u64 v[66:67], v[64:65], 0, v[72:73]
	v_mov_b32_e32 v72, s57
	v_lshl_add_u64 v[68:69], v[64:65], 0, v[72:73]
	v_mov_b32_e32 v70, 0x2000
	v_mov_b32_e32 v71, 0
	global_load_dwordx4 v[180:183], v[64:65], off
	global_load_dwordx4 v[184:187], v[66:67], off
	global_load_dwordx4 v[188:191], v[68:69], off
	v_lshl_add_u64 v[64:65], v[64:65], 0, v[70:71]
	v_lshl_add_u64 v[66:67], v[66:67], 0, v[70:71]
	v_lshl_add_u64 v[68:69], v[68:69], 0, v[70:71]
	global_load_dwordx4 v[192:195], v[64:65], off
	global_load_dwordx4 v[196:199], v[66:67], off
	global_load_dwordx4 v[200:203], v[68:69], off
	v_lshl_add_u64 v[64:65], v[64:65], 0, v[70:71]
	v_lshl_add_u64 v[66:67], v[66:67], 0, v[70:71]
	v_lshl_add_u64 v[68:69], v[68:69], 0, v[70:71]
	global_load_dwordx4 v[204:207], v[64:65], off
	global_load_dwordx4 v[208:211], v[66:67], off
	global_load_dwordx4 v[212:215], v[68:69], off
	v_lshl_add_u64 v[64:65], v[64:65], 0, v[70:71]
	v_lshl_add_u64 v[66:67], v[66:67], 0, v[70:71]
	v_lshl_add_u64 v[68:69], v[68:69], 0, v[70:71]
	global_load_dwordx4 v[216:219], v[64:65], off
	global_load_dwordx4 v[220:223], v[66:67], off
	global_load_dwordx4 v[60:63], v[68:69], off
	s_waitcnt vmcnt(0)
	s_nop 1
	v_mov_b64_e32 v[8:9], v[34:35]
	s_nop 0
	s_nop 1
	v_mov_b64_e32 v[10:11], v[36:37]
	s_nop 0
	s_nop 1
	v_mov_b64_e32 v[2:3], v[38:39]
	s_nop 0
	v_max3_f32 v12, v8, v10, v2
	v_sub_f32_e32 v8, v8, v12
	v_sub_f32_e32 v10, v10, v12
	v_sub_f32_e32 v2, v2, v12
	v_exp_f32_e32 v8, v8
	v_exp_f32_e32 v13, v10
	v_exp_f32_e32 v12, v2
	v_mov_b32_e32 v10, v3
	v_fma_f32 v2, v9, v8, 0
	v_mul_f32_e32 v14, v9, v8
	v_pk_mul_f32 v[20:21], v[10:11], v[12:13]
	s_nop 0
	v_add_f32_e32 v2, v21, v2
	v_add_f32_e32 v2, v20, v2
	v_div_scale_f32 v3, s[20:21], v2, v2, 1.0
	v_rcp_f32_e32 v8, v3
	s_nop 0
	v_fma_f32 v9, -v3, v8, 1.0
	v_fmac_f32_e32 v8, v9, v8
	v_div_scale_f32 v9, vcc, 1.0, v2, 1.0
	v_mul_f32_e32 v10, v9, v8
	v_fma_f32 v11, -v3, v10, v9
	v_fmac_f32_e32 v10, v11, v8
	v_fma_f32 v3, -v3, v10, v9
	v_div_fmas_f32 v3, v3, v8, v10
	v_div_fixup_f32 v23, v3, v2, 1.0
	v_lshlrev_b64 v[2:3], 11, v[4:5]
	v_lshl_add_u64 v[8:9], s[10:11], 0, v[2:3]
	v_and_b32_e32 v2, 0x3f8, v7
	v_lshlrev_b32_e32 v2, 1, v2
	v_mov_b32_e32 v3, v83
	v_lshl_add_u64 v[16:17], v[8:9], 0, v[2:3]
	v_add_co_u32_e32 v12, vcc, s56, v16
	s_nop 1
	v_mov_b64_e32 v[8:9], v[180:181]
	v_mov_b64_e32 v[10:11], v[182:183]
	s_nop 0
	v_addc_co_u32_e32 v13, vcc, 0, v17, vcc
	v_mul_f32_e32 v22, v14, v23
	s_nop 1
	v_mov_b64_e32 v[12:13], v[184:185]
	v_mov_b64_e32 v[14:15], v[186:187]
	v_add_co_u32_e32 v16, vcc, s57, v16
	v_mul_f32_e32 v24, v21, v23
	s_nop 0
	v_addc_co_u32_e32 v17, vcc, 0, v17, vcc
	s_nop 1
	v_mov_b64_e32 v[16:17], v[188:189]
	v_mov_b64_e32 v[18:19], v[190:191]
	v_mul_f32_e32 v20, v20, v23
	v_lshlrev_b64 v[4:5], 12, v[4:5]
	v_lshl_add_u64 v[4:5], s[88:89], 0, v[4:5]
	v_lshl_add_u64 v[4:5], v[4:5], 0, v[2:3]
	v_add_co_u32_e32 v4, vcc, s62, v4
	v_add_u32_e32 v7, 0x4000, v7
	s_nop 0
	v_addc_co_u32_e32 v5, vcc, 0, v5, vcc
	s_nop 0
	v_lshlrev_b32_e32 v27, 16, v9
	v_lshlrev_b32_e32 v26, 16, v8
	v_and_b32_e32 v9, 0xffff0000, v9
	v_and_b32_e32 v8, 0xffff0000, v8
	v_pk_fma_f32 v[8:9], v[22:23], v[8:9], 0 op_sel_hi:[0,1,0]
	s_nop 0
	v_lshlrev_b32_e32 v29, 16, v13
	v_lshlrev_b32_e32 v28, 16, v12
	v_and_b32_e32 v13, 0xffff0000, v13
	v_and_b32_e32 v12, 0xffff0000, v12
	v_pk_fma_f32 v[8:9], v[24:25], v[12:13], v[8:9] op_sel_hi:[0,1,1]
	s_nop 0
	v_lshlrev_b32_e32 v13, 16, v17
	v_lshlrev_b32_e32 v12, 16, v16
	v_and_b32_e32 v17, 0xffff0000, v17
	v_and_b32_e32 v16, 0xffff0000, v16
	v_pk_fma_f32 v[8:9], v[20:21], v[16:17], v[8:9] op_sel_hi:[0,1,1]
	v_lshlrev_b32_e32 v17, 16, v11
	v_lshlrev_b32_e32 v16, 16, v10
	v_and_b32_e32 v11, 0xffff0000, v11
	v_and_b32_e32 v10, 0xffff0000, v10
	v_pk_fma_f32 v[26:27], v[22:23], v[26:27], 0 op_sel_hi:[0,1,0]
	v_pk_fma_f32 v[16:17], v[22:23], v[16:17], 0 op_sel_hi:[0,1,0]
	v_pk_fma_f32 v[10:11], v[22:23], v[10:11], 0 op_sel_hi:[0,1,0]
	v_lshlrev_b32_e32 v23, 16, v15
	v_lshlrev_b32_e32 v22, 16, v14
	v_and_b32_e32 v15, 0xffff0000, v15
	v_and_b32_e32 v14, 0xffff0000, v14
	v_pk_fma_f32 v[16:17], v[24:25], v[22:23], v[16:17] op_sel_hi:[0,1,1]
	v_pk_fma_f32 v[10:11], v[24:25], v[14:15], v[10:11] op_sel_hi:[0,1,1]
	v_lshlrev_b32_e32 v15, 16, v19
	v_lshlrev_b32_e32 v14, 16, v18
	v_pk_fma_f32 v[14:15], v[20:21], v[14:15], v[16:17] op_sel_hi:[0,1,1]
	v_and_b32_e32 v17, 0xffff0000, v19
	v_and_b32_e32 v16, 0xffff0000, v18
	v_pk_fma_f32 v[26:27], v[24:25], v[28:29], v[26:27] op_sel_hi:[0,1,1]
	v_pk_fma_f32 v[10:11], v[20:21], v[16:17], v[10:11] op_sel_hi:[0,1,1]
	v_pk_fma_f32 v[12:13], v[20:21], v[12:13], v[26:27] op_sel_hi:[0,1,1]
	v_cvt_pk_bf16_f32 v11, v15, v11
	v_cvt_pk_bf16_f32 v10, v14, v10
	v_cvt_pk_bf16_f32 v9, v13, v9
	v_cvt_pk_bf16_f32 v8, v12, v8
	global_store_dwordx4 v[4:5], v[8:11], off offset:2048
	v_add_u32_e32 v4, 0x200, v6
	v_ashrrev_i32_e32 v4, 7, v4
	v_ashrrev_i32_e32 v5, 31, v4
	v_lshlrev_b64 v[8:9], 6, v[4:5]
	v_lshl_add_u64 v[10:11], s[12:13], 0, v[8:9]
	v_lshl_add_u64 v[12:13], s[14:15], 0, v[8:9]
	v_lshl_add_u64 v[8:9], s[16:17], 0, v[8:9]
	v_lshl_add_u64 v[10:11], v[10:11], 0, v[82:83]
	v_lshl_add_u64 v[12:13], v[12:13], 0, v[82:83]
	v_lshl_add_u64 v[8:9], v[8:9], 0, v[82:83]
	s_nop 1
	v_mov_b64_e32 v[10:11], v[40:41]
	s_nop 0
	s_nop 1
	v_mov_b64_e32 v[12:13], v[42:43]
	s_nop 0
	s_nop 1
	v_mov_b64_e32 v[8:9], v[44:45]
	s_nop 0
	v_max3_f32 v14, v10, v12, v8
	v_sub_f32_e32 v10, v10, v14
	v_sub_f32_e32 v12, v12, v14
	v_sub_f32_e32 v8, v8, v14
	v_exp_f32_e32 v10, v10
	v_exp_f32_e32 v15, v12
	v_exp_f32_e32 v14, v8
	v_mov_b32_e32 v12, v9
	v_fma_f32 v8, v11, v10, 0
	v_mul_f32_e32 v18, v11, v10
	v_pk_mul_f32 v[20:21], v[12:13], v[14:15]
	s_nop 0
	v_add_f32_e32 v8, v21, v8
	v_add_f32_e32 v8, v20, v8
	v_div_scale_f32 v9, s[20:21], v8, v8, 1.0
	v_rcp_f32_e32 v10, v9
	s_nop 0
	v_fma_f32 v11, -v9, v10, 1.0
	v_fmac_f32_e32 v10, v11, v10
	v_div_scale_f32 v11, vcc, 1.0, v8, 1.0
	v_mul_f32_e32 v12, v11, v10
	v_fma_f32 v13, -v9, v12, v11
	v_fmac_f32_e32 v12, v13, v10
	v_fma_f32 v9, -v9, v12, v11
	v_div_fmas_f32 v9, v9, v10, v12
	v_div_fixup_f32 v23, v9, v8, 1.0
	v_lshlrev_b64 v[8:9], 11, v[4:5]
	v_lshl_add_u64 v[8:9], s[10:11], 0, v[8:9]
	v_lshl_add_u64 v[16:17], v[8:9], 0, v[2:3]
	v_add_co_u32_e32 v12, vcc, s56, v16
	s_nop 1
	v_mov_b64_e32 v[8:9], v[192:193]
	v_mov_b64_e32 v[10:11], v[194:195]
	s_nop 0
	v_addc_co_u32_e32 v13, vcc, 0, v17, vcc
	s_nop 1
	v_mov_b64_e32 v[12:13], v[196:197]
	v_mov_b64_e32 v[14:15], v[198:199]
	v_add_co_u32_e32 v16, vcc, s57, v16
	v_mul_f32_e32 v22, v18, v23
	s_nop 0
	v_addc_co_u32_e32 v17, vcc, 0, v17, vcc
	s_nop 1
	v_mov_b64_e32 v[16:17], v[200:201]
	v_mov_b64_e32 v[18:19], v[202:203]
	v_mul_f32_e32 v24, v21, v23
	v_mul_f32_e32 v20, v20, v23
	v_lshlrev_b64 v[4:5], 12, v[4:5]
	v_lshl_add_u64 v[4:5], s[88:89], 0, v[4:5]
	v_lshl_add_u64 v[4:5], v[4:5], 0, v[2:3]
	v_add_co_u32_e32 v4, vcc, s62, v4
	s_nop 0
	v_lshlrev_b32_e32 v27, 16, v9
	v_lshlrev_b32_e32 v26, 16, v8
	v_and_b32_e32 v9, 0xffff0000, v9
	v_and_b32_e32 v8, 0xffff0000, v8
	v_pk_fma_f32 v[8:9], v[22:23], v[8:9], 0 op_sel_hi:[0,1,0]
	s_nop 0
	v_lshlrev_b32_e32 v29, 16, v13
	v_lshlrev_b32_e32 v28, 16, v12
	v_and_b32_e32 v13, 0xffff0000, v13
	v_and_b32_e32 v12, 0xffff0000, v12
	v_pk_fma_f32 v[8:9], v[24:25], v[12:13], v[8:9] op_sel_hi:[0,1,1]
	s_nop 0
	v_lshlrev_b32_e32 v13, 16, v17
	v_lshlrev_b32_e32 v12, 16, v16
	v_and_b32_e32 v17, 0xffff0000, v17
	v_and_b32_e32 v16, 0xffff0000, v16
	v_pk_fma_f32 v[8:9], v[20:21], v[16:17], v[8:9] op_sel_hi:[0,1,1]
	v_lshlrev_b32_e32 v17, 16, v11
	v_lshlrev_b32_e32 v16, 16, v10
	v_and_b32_e32 v11, 0xffff0000, v11
	v_and_b32_e32 v10, 0xffff0000, v10
	v_pk_fma_f32 v[26:27], v[22:23], v[26:27], 0 op_sel_hi:[0,1,0]
	v_pk_fma_f32 v[16:17], v[22:23], v[16:17], 0 op_sel_hi:[0,1,0]
	v_pk_fma_f32 v[10:11], v[22:23], v[10:11], 0 op_sel_hi:[0,1,0]
	v_lshlrev_b32_e32 v23, 16, v15
	v_lshlrev_b32_e32 v22, 16, v14
	v_and_b32_e32 v15, 0xffff0000, v15
	v_and_b32_e32 v14, 0xffff0000, v14
	v_pk_fma_f32 v[16:17], v[24:25], v[22:23], v[16:17] op_sel_hi:[0,1,1]
	v_pk_fma_f32 v[10:11], v[24:25], v[14:15], v[10:11] op_sel_hi:[0,1,1]
	v_lshlrev_b32_e32 v15, 16, v19
	v_lshlrev_b32_e32 v14, 16, v18
	v_pk_fma_f32 v[14:15], v[20:21], v[14:15], v[16:17] op_sel_hi:[0,1,1]
	v_and_b32_e32 v17, 0xffff0000, v19
	v_and_b32_e32 v16, 0xffff0000, v18
	v_pk_fma_f32 v[26:27], v[24:25], v[28:29], v[26:27] op_sel_hi:[0,1,1]
	v_pk_fma_f32 v[10:11], v[20:21], v[16:17], v[10:11] op_sel_hi:[0,1,1]
	v_pk_fma_f32 v[12:13], v[20:21], v[12:13], v[26:27] op_sel_hi:[0,1,1]
	v_cvt_pk_bf16_f32 v11, v15, v11
	v_cvt_pk_bf16_f32 v10, v14, v10
	v_cvt_pk_bf16_f32 v9, v13, v9
	v_cvt_pk_bf16_f32 v8, v12, v8
	v_addc_co_u32_e32 v5, vcc, 0, v5, vcc
	global_store_dwordx4 v[4:5], v[8:11], off offset:2048
	v_add_u32_e32 v4, 0x400, v6
	v_ashrrev_i32_e32 v4, 7, v4
	v_ashrrev_i32_e32 v5, 31, v4
	v_lshlrev_b64 v[8:9], 6, v[4:5]
	v_lshl_add_u64 v[10:11], s[12:13], 0, v[8:9]
	v_lshl_add_u64 v[12:13], s[14:15], 0, v[8:9]
	v_lshl_add_u64 v[8:9], s[16:17], 0, v[8:9]
	v_lshl_add_u64 v[10:11], v[10:11], 0, v[82:83]
	v_lshl_add_u64 v[12:13], v[12:13], 0, v[82:83]
	v_lshl_add_u64 v[8:9], v[8:9], 0, v[82:83]
	s_nop 1
	v_mov_b64_e32 v[10:11], v[46:47]
	s_nop 0
	s_nop 1
	v_mov_b64_e32 v[12:13], v[48:49]
	s_nop 0
	s_nop 1
	v_mov_b64_e32 v[8:9], v[50:51]
	s_nop 0
	v_max3_f32 v14, v10, v12, v8
	v_sub_f32_e32 v10, v10, v14
	v_sub_f32_e32 v12, v12, v14
	v_sub_f32_e32 v8, v8, v14
	v_exp_f32_e32 v10, v10
	v_exp_f32_e32 v15, v12
	v_exp_f32_e32 v14, v8
	v_mov_b32_e32 v12, v9
	v_fma_f32 v8, v11, v10, 0
	v_mul_f32_e32 v18, v11, v10
	v_pk_mul_f32 v[20:21], v[12:13], v[14:15]
	s_nop 0
	v_add_f32_e32 v8, v21, v8
	v_add_f32_e32 v8, v20, v8
	v_div_scale_f32 v9, s[20:21], v8, v8, 1.0
	v_rcp_f32_e32 v10, v9
	s_nop 0
	v_fma_f32 v11, -v9, v10, 1.0
	v_fmac_f32_e32 v10, v11, v10
	v_div_scale_f32 v11, vcc, 1.0, v8, 1.0
	v_mul_f32_e32 v12, v11, v10
	v_fma_f32 v13, -v9, v12, v11
	v_fmac_f32_e32 v12, v13, v10
	v_fma_f32 v9, -v9, v12, v11
	v_div_fmas_f32 v9, v9, v10, v12
	v_div_fixup_f32 v23, v9, v8, 1.0
	v_lshlrev_b64 v[8:9], 11, v[4:5]
	v_lshl_add_u64 v[8:9], s[10:11], 0, v[8:9]
	v_lshl_add_u64 v[16:17], v[8:9], 0, v[2:3]
	v_add_co_u32_e32 v12, vcc, s56, v16
	s_nop 1
	v_mov_b64_e32 v[8:9], v[204:205]
	v_mov_b64_e32 v[10:11], v[206:207]
	s_nop 0
	v_addc_co_u32_e32 v13, vcc, 0, v17, vcc
	s_nop 1
	v_mov_b64_e32 v[12:13], v[208:209]
	v_mov_b64_e32 v[14:15], v[210:211]
	v_add_co_u32_e32 v16, vcc, s57, v16
	v_mul_f32_e32 v22, v18, v23
	s_nop 0
	v_addc_co_u32_e32 v17, vcc, 0, v17, vcc
	s_nop 1
	v_mov_b64_e32 v[16:17], v[212:213]
	v_mov_b64_e32 v[18:19], v[214:215]
	v_mul_f32_e32 v24, v21, v23
	v_mul_f32_e32 v20, v20, v23
	v_lshlrev_b64 v[4:5], 12, v[4:5]
	v_lshl_add_u64 v[4:5], s[88:89], 0, v[4:5]
	v_lshl_add_u64 v[4:5], v[4:5], 0, v[2:3]
	v_add_co_u32_e32 v4, vcc, s62, v4
	s_nop 0
	v_lshlrev_b32_e32 v27, 16, v9
	v_lshlrev_b32_e32 v26, 16, v8
	v_and_b32_e32 v9, 0xffff0000, v9
	v_and_b32_e32 v8, 0xffff0000, v8
	v_pk_fma_f32 v[8:9], v[22:23], v[8:9], 0 op_sel_hi:[0,1,0]
	s_nop 0
	v_lshlrev_b32_e32 v29, 16, v13
	v_lshlrev_b32_e32 v28, 16, v12
	v_and_b32_e32 v13, 0xffff0000, v13
	v_and_b32_e32 v12, 0xffff0000, v12
	v_pk_fma_f32 v[8:9], v[24:25], v[12:13], v[8:9] op_sel_hi:[0,1,1]
	s_nop 0
	v_lshlrev_b32_e32 v13, 16, v17
	v_lshlrev_b32_e32 v12, 16, v16
	v_and_b32_e32 v17, 0xffff0000, v17
	v_and_b32_e32 v16, 0xffff0000, v16
	v_pk_fma_f32 v[8:9], v[20:21], v[16:17], v[8:9] op_sel_hi:[0,1,1]
	v_lshlrev_b32_e32 v17, 16, v11
	v_lshlrev_b32_e32 v16, 16, v10
	v_and_b32_e32 v11, 0xffff0000, v11
	v_and_b32_e32 v10, 0xffff0000, v10
	v_pk_fma_f32 v[26:27], v[22:23], v[26:27], 0 op_sel_hi:[0,1,0]
	v_pk_fma_f32 v[16:17], v[22:23], v[16:17], 0 op_sel_hi:[0,1,0]
	v_pk_fma_f32 v[10:11], v[22:23], v[10:11], 0 op_sel_hi:[0,1,0]
	v_lshlrev_b32_e32 v23, 16, v15
	v_lshlrev_b32_e32 v22, 16, v14
	v_and_b32_e32 v15, 0xffff0000, v15
	v_and_b32_e32 v14, 0xffff0000, v14
	v_pk_fma_f32 v[16:17], v[24:25], v[22:23], v[16:17] op_sel_hi:[0,1,1]
	v_pk_fma_f32 v[10:11], v[24:25], v[14:15], v[10:11] op_sel_hi:[0,1,1]
	v_lshlrev_b32_e32 v15, 16, v19
	v_lshlrev_b32_e32 v14, 16, v18
	v_pk_fma_f32 v[14:15], v[20:21], v[14:15], v[16:17] op_sel_hi:[0,1,1]
	v_and_b32_e32 v17, 0xffff0000, v19
	v_and_b32_e32 v16, 0xffff0000, v18
	v_pk_fma_f32 v[26:27], v[24:25], v[28:29], v[26:27] op_sel_hi:[0,1,1]
	v_pk_fma_f32 v[10:11], v[20:21], v[16:17], v[10:11] op_sel_hi:[0,1,1]
	v_pk_fma_f32 v[12:13], v[20:21], v[12:13], v[26:27] op_sel_hi:[0,1,1]
	v_cvt_pk_bf16_f32 v11, v15, v11
	v_cvt_pk_bf16_f32 v10, v14, v10
	v_cvt_pk_bf16_f32 v9, v13, v9
	v_cvt_pk_bf16_f32 v8, v12, v8
	v_addc_co_u32_e32 v5, vcc, 0, v5, vcc
	global_store_dwordx4 v[4:5], v[8:11], off offset:2048
	v_add_u32_e32 v4, 0x600, v6
	v_ashrrev_i32_e32 v4, 7, v4
	v_ashrrev_i32_e32 v5, 31, v4
	v_lshlrev_b64 v[8:9], 6, v[4:5]
	v_lshl_add_u64 v[10:11], s[12:13], 0, v[8:9]
	v_lshl_add_u64 v[12:13], s[14:15], 0, v[8:9]
	v_lshl_add_u64 v[8:9], s[16:17], 0, v[8:9]
	v_lshl_add_u64 v[10:11], v[10:11], 0, v[82:83]
	v_lshl_add_u64 v[12:13], v[12:13], 0, v[82:83]
	v_lshl_add_u64 v[8:9], v[8:9], 0, v[82:83]
	s_nop 1
	v_mov_b64_e32 v[10:11], v[52:53]
	v_add_u32_e32 v6, 0x800, v6
	s_nop 1
	v_mov_b64_e32 v[12:13], v[54:55]
	s_nop 0
	s_nop 1
	v_mov_b64_e32 v[8:9], v[56:57]
	s_nop 0
	v_max3_f32 v14, v10, v12, v8
	v_sub_f32_e32 v10, v10, v14
	v_sub_f32_e32 v12, v12, v14
	v_sub_f32_e32 v8, v8, v14
	v_exp_f32_e32 v10, v10
	v_exp_f32_e32 v15, v12
	v_exp_f32_e32 v14, v8
	v_mov_b32_e32 v12, v9
	v_fma_f32 v8, v11, v10, 0
	v_mul_f32_e32 v18, v11, v10
	v_pk_mul_f32 v[20:21], v[12:13], v[14:15]
	s_nop 0
	v_add_f32_e32 v8, v21, v8
	v_add_f32_e32 v8, v20, v8
	v_div_scale_f32 v9, s[20:21], v8, v8, 1.0
	v_rcp_f32_e32 v10, v9
	s_nop 0
	v_fma_f32 v11, -v9, v10, 1.0
	v_fmac_f32_e32 v10, v11, v10
	v_div_scale_f32 v11, vcc, 1.0, v8, 1.0
	v_mul_f32_e32 v12, v11, v10
	v_fma_f32 v13, -v9, v12, v11
	v_fmac_f32_e32 v12, v13, v10
	v_fma_f32 v9, -v9, v12, v11
	v_div_fmas_f32 v9, v9, v10, v12
	v_div_fixup_f32 v23, v9, v8, 1.0
	v_lshlrev_b64 v[8:9], 11, v[4:5]
	v_lshl_add_u64 v[8:9], s[10:11], 0, v[8:9]
	v_lshl_add_u64 v[16:17], v[8:9], 0, v[2:3]
	v_add_co_u32_e32 v12, vcc, s56, v16
	s_nop 1
	v_mov_b64_e32 v[8:9], v[216:217]
	v_mov_b64_e32 v[10:11], v[218:219]
	s_nop 0
	v_addc_co_u32_e32 v13, vcc, 0, v17, vcc
	s_nop 1
	v_mov_b64_e32 v[12:13], v[220:221]
	v_mov_b64_e32 v[14:15], v[222:223]
	v_add_co_u32_e32 v16, vcc, s57, v16
	v_mul_f32_e32 v22, v18, v23
	s_nop 0
	v_addc_co_u32_e32 v17, vcc, 0, v17, vcc
	s_nop 1
	v_mov_b64_e32 v[16:17], v[60:61]
	v_mov_b64_e32 v[18:19], v[62:63]
	v_mul_f32_e32 v24, v21, v23
	v_mul_f32_e32 v20, v20, v23
	v_lshlrev_b64 v[4:5], 12, v[4:5]
	v_lshl_add_u64 v[4:5], s[88:89], 0, v[4:5]
	v_lshl_add_u64 v[2:3], v[4:5], 0, v[2:3]
	v_add_co_u32_e32 v2, vcc, 0x1b81e000, v2
	s_nop 0
	v_lshlrev_b32_e32 v27, 16, v9
	v_lshlrev_b32_e32 v26, 16, v8
	v_and_b32_e32 v9, 0xffff0000, v9
	v_and_b32_e32 v8, 0xffff0000, v8
	v_pk_fma_f32 v[8:9], v[22:23], v[8:9], 0 op_sel_hi:[0,1,0]
	s_nop 0
	v_lshlrev_b32_e32 v29, 16, v13
	v_lshlrev_b32_e32 v28, 16, v12
	v_and_b32_e32 v13, 0xffff0000, v13
	v_and_b32_e32 v12, 0xffff0000, v12
	v_pk_fma_f32 v[8:9], v[24:25], v[12:13], v[8:9] op_sel_hi:[0,1,1]
	s_nop 0
	v_lshlrev_b32_e32 v13, 16, v17
	v_lshlrev_b32_e32 v12, 16, v16
	v_and_b32_e32 v17, 0xffff0000, v17
	v_and_b32_e32 v16, 0xffff0000, v16
	v_pk_fma_f32 v[8:9], v[20:21], v[16:17], v[8:9] op_sel_hi:[0,1,1]
	v_lshlrev_b32_e32 v17, 16, v11
	v_lshlrev_b32_e32 v16, 16, v10
	v_and_b32_e32 v11, 0xffff0000, v11
	v_and_b32_e32 v10, 0xffff0000, v10
	v_pk_fma_f32 v[26:27], v[22:23], v[26:27], 0 op_sel_hi:[0,1,0]
	v_pk_fma_f32 v[16:17], v[22:23], v[16:17], 0 op_sel_hi:[0,1,0]
	v_pk_fma_f32 v[10:11], v[22:23], v[10:11], 0 op_sel_hi:[0,1,0]
	v_lshlrev_b32_e32 v23, 16, v15
	v_lshlrev_b32_e32 v22, 16, v14
	v_and_b32_e32 v15, 0xffff0000, v15
	v_and_b32_e32 v14, 0xffff0000, v14
	v_pk_fma_f32 v[16:17], v[24:25], v[22:23], v[16:17] op_sel_hi:[0,1,1]
	v_pk_fma_f32 v[10:11], v[24:25], v[14:15], v[10:11] op_sel_hi:[0,1,1]
	v_lshlrev_b32_e32 v15, 16, v19
	v_lshlrev_b32_e32 v14, 16, v18
	v_pk_fma_f32 v[14:15], v[20:21], v[14:15], v[16:17] op_sel_hi:[0,1,1]
	v_and_b32_e32 v17, 0xffff0000, v19
	v_and_b32_e32 v16, 0xffff0000, v18
	v_pk_fma_f32 v[26:27], v[24:25], v[28:29], v[26:27] op_sel_hi:[0,1,1]
	v_pk_fma_f32 v[10:11], v[20:21], v[16:17], v[10:11] op_sel_hi:[0,1,1]
	v_pk_fma_f32 v[12:13], v[20:21], v[12:13], v[26:27] op_sel_hi:[0,1,1]
	v_bfe_u32 v16, v11, 16, 1
	v_bfe_u32 v17, v10, 16, 1
	v_bfe_u32 v18, v9, 16, 1
	v_bfe_u32 v19, v8, 16, 1
	v_add3_u32 v8, v8, v19, s73
	v_add3_u32 v9, v9, v18, s73
	v_add3_u32 v10, v10, v17, s73
	v_add3_u32 v11, v11, v16, s73
	v_bfe_u32 v16, v12, 16, 1
	v_bfe_u32 v17, v13, 16, 1
	v_bfe_u32 v18, v14, 16, 1
	v_bfe_u32 v19, v15, 16, 1
	v_add3_u32 v15, v15, v19, s73
	v_add3_u32 v14, v14, v18, s73
	v_add3_u32 v13, v13, v17, s73
	v_add3_u32 v12, v12, v16, s73
	v_addc_co_u32_e32 v3, vcc, 0, v3, vcc
	v_lshrrev_b32_e32 v12, 16, v12
	v_lshrrev_b32_e32 v13, 16, v13
	v_lshrrev_b32_e32 v14, 16, v14
	v_lshrrev_b32_e32 v15, 16, v15
	v_cmp_le_i32_e32 vcc, s22, v6
	v_and_or_b32 v11, v11, s33, v15
	v_and_or_b32 v10, v10, s33, v14
	v_and_or_b32 v9, v9, s33, v13
	v_and_or_b32 v8, v8, s33, v12
	s_or_b64 s[18:19], vcc, s[18:19]
	global_store_dwordx4 v[2:3], v[8:11], off offset:2048
	s_andn2_b64 exec, exec, s[18:19]
	s_cbranch_execnz .LBB0_1018
